# GEMM K-loop MMA blocks: staged lgkmcnt waits (each MFMA pair waits only for the LDS fragment it reads) instead of lgkmcnt(0) before the block
# speedup vs baseline: 1.0006x; 1.0006x over previous
.LBB0_141:
	s_add_i32 s72, s40, 2
	s_add_u32 s68, s0, 0x80
	s_addc_u32 s41, s1, 0
	s_add_i32 s73, 0, 0x10000
	v_add_u32_e32 v140, s73, v183
	ds_read_b128 v[128:131], v140
	ds_read_b128 v[132:135], v140 offset:1024
	ds_read_b128 v[136:139], v140 offset:2048
	ds_read_b128 v[140:143], v140 offset:3072
	s_cmp_eq_u32 s10, s40
	s_cselect_b32 s40, s64, s68
	s_cselect_b32 s41, s65, s41
	s_cselect_b32 s69, s67, s71
	s_cselect_b32 s68, s66, s70
	v_lshl_add_u64 v[176:177], s[0:1], 0, v[192:193]
	s_add_i32 m0, s76, 0xc000
	ds_read_b128 v[144:147], v239
	ds_read_b128 v[148:151], v239 offset:1024
	ds_read_b128 v[152:155], v239 offset:2048
	ds_read_b128 v[156:159], v239 offset:3072
	ds_read_b128 v[160:163], v239 offset:4096
	ds_read_b128 v[164:167], v239 offset:5120
	ds_read_b128 v[168:171], v239 offset:6144
	ds_read_b128 v[172:175], v239 offset:7168
	global_load_lds_dwordx4 v[176:177], off
	v_lshl_add_u64 v[176:177], s[0:1], 0, v[194:195]
	s_add_i32 m0, s76, 0xe000
	s_nop 0
	global_load_lds_dwordx4 v[176:177], off
	s_waitcnt lgkmcnt(8)
	s_barrier
	s_waitcnt lgkmcnt(7)
	v_mfma_f32_16x16x32_bf16 v[124:127], v[128:131], v[144:147], v[124:127]
	v_mfma_f32_16x16x32_bf16 v[116:119], v[136:139], v[144:147], v[116:119]
	s_waitcnt lgkmcnt(5)
	v_mfma_f32_16x16x32_bf16 v[108:111], v[128:131], v[152:155], v[108:111]
	v_mfma_f32_16x16x32_bf16 v[100:103], v[136:139], v[152:155], v[100:103]
	s_waitcnt lgkmcnt(3)
	v_mfma_f32_16x16x32_bf16 v[92:95], v[128:131], v[160:163], v[92:95]
	v_mfma_f32_16x16x32_bf16 v[84:87], v[136:139], v[160:163], v[84:87]
	s_waitcnt lgkmcnt(1)
	v_mfma_f32_16x16x32_bf16 v[76:79], v[128:131], v[168:171], v[76:79]
	v_mfma_f32_16x16x32_bf16 v[68:71], v[136:139], v[168:171], v[68:71]
	v_mfma_f32_16x16x32_bf16 v[124:127], v[132:135], v[148:151], v[124:127]
	v_mfma_f32_16x16x32_bf16 v[116:119], v[140:143], v[148:151], v[116:119]
	v_mfma_f32_16x16x32_bf16 v[108:111], v[132:135], v[156:159], v[108:111]
	v_mfma_f32_16x16x32_bf16 v[100:103], v[140:143], v[156:159], v[100:103]
	v_mfma_f32_16x16x32_bf16 v[92:95], v[132:135], v[164:167], v[92:95]
	v_mfma_f32_16x16x32_bf16 v[84:87], v[140:143], v[164:167], v[84:87]
	s_waitcnt lgkmcnt(0)
	v_mfma_f32_16x16x32_bf16 v[76:79], v[132:135], v[172:175], v[76:79]
	v_mfma_f32_16x16x32_bf16 v[68:71], v[140:143], v[172:175], v[68:71]
	s_barrier
	s_add_i32 s80, 0, 0x14000
	s_add_i32 s73, s73, s33
	v_add_u32_e32 v204, s80, v183
	v_lshl_add_u64 v[208:209], s[68:69], 0, v[186:187]
	s_mov_b32 m0, s73
	ds_read_b128 v[176:179], v204
	ds_read_b128 v[196:199], v204 offset:1024
	ds_read_b128 v[200:203], v204 offset:2048
	ds_read_b128 v[204:207], v204 offset:3072
	global_load_lds_dwordx4 v[208:209], off
	v_lshl_add_u64 v[210:211], s[68:69], 0, v[190:191]
	s_add_i32 m0, s73, 0x2000
	s_nop 0
	global_load_lds_dwordx4 v[210:211], off
	s_barrier
	s_waitcnt lgkmcnt(3)
	v_mfma_f32_16x16x32_bf16 v[120:123], v[176:179], v[144:147], v[120:123]
	s_waitcnt lgkmcnt(1)
	v_mfma_f32_16x16x32_bf16 v[112:115], v[200:203], v[144:147], v[112:115]
	v_mfma_f32_16x16x32_bf16 v[104:107], v[176:179], v[152:155], v[104:107]
	v_mfma_f32_16x16x32_bf16 v[96:99], v[200:203], v[152:155], v[96:99]
	v_mfma_f32_16x16x32_bf16 v[88:91], v[176:179], v[160:163], v[88:91]
	v_mfma_f32_16x16x32_bf16 v[80:83], v[200:203], v[160:163], v[80:83]
	v_mfma_f32_16x16x32_bf16 v[72:75], v[176:179], v[168:171], v[72:75]
	v_mfma_f32_16x16x32_bf16 v[64:67], v[200:203], v[168:171], v[64:67]
	v_mfma_f32_16x16x32_bf16 v[120:123], v[196:199], v[148:151], v[120:123]
	s_waitcnt lgkmcnt(0)
	v_mfma_f32_16x16x32_bf16 v[112:115], v[204:207], v[148:151], v[112:115]
	v_mfma_f32_16x16x32_bf16 v[104:107], v[196:199], v[156:159], v[104:107]
	v_mfma_f32_16x16x32_bf16 v[96:99], v[204:207], v[156:159], v[96:99]
	v_mfma_f32_16x16x32_bf16 v[88:91], v[196:199], v[164:167], v[88:91]
	v_mfma_f32_16x16x32_bf16 v[80:83], v[204:207], v[164:167], v[80:83]
	v_mfma_f32_16x16x32_bf16 v[72:75], v[196:199], v[172:175], v[72:75]
	v_mfma_f32_16x16x32_bf16 v[64:67], v[204:207], v[172:175], v[64:67]
	s_mov_b32 m0, s76
	v_lshl_add_u64 v[212:213], s[40:41], 0, v[184:185]
	s_barrier
	ds_read_b128 v[144:147], v239 offset:16384
	ds_read_b128 v[148:151], v239 offset:17408
	ds_read_b128 v[152:155], v239 offset:18432
	ds_read_b128 v[156:159], v239 offset:19456
	ds_read_b128 v[160:163], v239 offset:20480
	ds_read_b128 v[164:167], v239 offset:21504
	ds_read_b128 v[168:171], v239 offset:22528
	ds_read_b128 v[172:175], v239 offset:23552
	global_load_lds_dwordx4 v[212:213], off
	v_lshl_add_u64 v[214:215], s[40:41], 0, v[188:189]
	s_mov_b32 m0, s4
	s_nop 0
	global_load_lds_dwordx4 v[214:215], off
	s_barrier
	s_waitcnt lgkmcnt(7)
	v_mfma_f32_16x16x32_bf16 v[60:63], v[128:131], v[144:147], v[60:63]
	v_mfma_f32_16x16x32_bf16 v[52:55], v[136:139], v[144:147], v[52:55]
	s_waitcnt lgkmcnt(5)
	v_mfma_f32_16x16x32_bf16 v[44:47], v[128:131], v[152:155], v[44:47]
	v_mfma_f32_16x16x32_bf16 v[36:39], v[136:139], v[152:155], v[36:39]
	s_waitcnt lgkmcnt(3)
	v_mfma_f32_16x16x32_bf16 v[28:31], v[128:131], v[160:163], v[28:31]
	v_mfma_f32_16x16x32_bf16 v[20:23], v[136:139], v[160:163], v[20:23]
	s_waitcnt lgkmcnt(1)
	v_mfma_f32_16x16x32_bf16 v[12:15], v[128:131], v[168:171], v[12:15]
	v_mfma_f32_16x16x32_bf16 v[4:7], v[136:139], v[168:171], v[4:7]
	v_mfma_f32_16x16x32_bf16 v[60:63], v[132:135], v[148:151], v[60:63]
	v_mfma_f32_16x16x32_bf16 v[52:55], v[140:143], v[148:151], v[52:55]
	v_mfma_f32_16x16x32_bf16 v[44:47], v[132:135], v[156:159], v[44:47]
	v_mfma_f32_16x16x32_bf16 v[36:39], v[140:143], v[156:159], v[36:39]
	v_mfma_f32_16x16x32_bf16 v[28:31], v[132:135], v[164:167], v[28:31]
	v_mfma_f32_16x16x32_bf16 v[20:23], v[140:143], v[164:167], v[20:23]
	s_waitcnt lgkmcnt(0)
	v_mfma_f32_16x16x32_bf16 v[12:15], v[132:135], v[172:175], v[12:15]
	v_mfma_f32_16x16x32_bf16 v[4:7], v[140:143], v[172:175], v[4:7]
	s_barrier
	s_add_u32 s68, s68, s98
	s_addc_u32 s69, s69, 0
	s_add_i32 s73, s80, s33
	v_lshl_add_u64 v[216:217], s[68:69], 0, v[186:187]
	s_mov_b32 m0, s73
	v_lshl_add_u64 v[218:219], s[68:69], 0, v[190:191]
	global_load_lds_dwordx4 v[216:217], off
	s_add_i32 m0, s73, 0x2000
	s_nop 0
	global_load_lds_dwordx4 v[218:219], off
	s_waitcnt vmcnt(6)
	s_barrier
	v_mfma_f32_16x16x32_bf16 v[56:59], v[176:179], v[144:147], v[56:59]
	v_mfma_f32_16x16x32_bf16 v[48:51], v[200:203], v[144:147], v[48:51]
	v_mfma_f32_16x16x32_bf16 v[40:43], v[176:179], v[152:155], v[40:43]
	v_mfma_f32_16x16x32_bf16 v[32:35], v[200:203], v[152:155], v[32:35]
	v_mfma_f32_16x16x32_bf16 v[24:27], v[176:179], v[160:163], v[24:27]
	v_mfma_f32_16x16x32_bf16 v[16:19], v[200:203], v[160:163], v[16:19]
	v_mfma_f32_16x16x32_bf16 v[8:11], v[176:179], v[168:171], v[8:11]
	v_mfma_f32_16x16x32_bf16 v[0:3], v[200:203], v[168:171], v[0:3]
	v_mfma_f32_16x16x32_bf16 v[56:59], v[196:199], v[148:151], v[56:59]
	v_mfma_f32_16x16x32_bf16 v[48:51], v[204:207], v[148:151], v[48:51]
	v_mfma_f32_16x16x32_bf16 v[40:43], v[196:199], v[156:159], v[40:43]
	v_mfma_f32_16x16x32_bf16 v[32:35], v[204:207], v[156:159], v[32:35]
	v_mfma_f32_16x16x32_bf16 v[24:27], v[196:199], v[164:167], v[24:27]
	v_mfma_f32_16x16x32_bf16 v[16:19], v[204:207], v[164:167], v[16:19]
	v_mfma_f32_16x16x32_bf16 v[8:11], v[196:199], v[172:175], v[8:11]
	v_mfma_f32_16x16x32_bf16 v[0:3], v[204:207], v[172:175], v[0:3]
	s_add_i32 s68, 0, 0x18000
	v_add_u32_e32 v140, s68, v183
	s_barrier
	ds_read_b128 v[128:131], v140
	ds_read_b128 v[132:135], v140 offset:1024
	ds_read_b128 v[136:139], v140 offset:2048
	ds_read_b128 v[140:143], v140 offset:3072
	s_add_u32 s40, s40, s98
	s_addc_u32 s41, s41, 0
	s_mov_b32 m0, s5
	v_lshl_add_u64 v[176:177], s[40:41], 0, v[184:185]
	ds_read_b128 v[144:147], v239 offset:32768
	ds_read_b128 v[148:151], v239 offset:33792
	ds_read_b128 v[152:155], v239 offset:34816
	ds_read_b128 v[156:159], v239 offset:35840
	ds_read_b128 v[160:163], v239 offset:36864
	ds_read_b128 v[164:167], v239 offset:37888
	ds_read_b128 v[168:171], v239 offset:38912
	ds_read_b128 v[172:175], v239 offset:39936
	global_load_lds_dwordx4 v[176:177], off
	v_lshl_add_u64 v[176:177], s[40:41], 0, v[188:189]
	s_mov_b32 m0, s6
	s_nop 0
	global_load_lds_dwordx4 v[176:177], off
	s_waitcnt lgkmcnt(8)
	s_barrier
	s_waitcnt lgkmcnt(7)
	v_mfma_f32_16x16x32_bf16 v[124:127], v[128:131], v[144:147], v[124:127]
	v_mfma_f32_16x16x32_bf16 v[116:119], v[136:139], v[144:147], v[116:119]
	s_waitcnt lgkmcnt(5)
	v_mfma_f32_16x16x32_bf16 v[108:111], v[128:131], v[152:155], v[108:111]
	v_mfma_f32_16x16x32_bf16 v[100:103], v[136:139], v[152:155], v[100:103]
	s_waitcnt lgkmcnt(3)
	v_mfma_f32_16x16x32_bf16 v[92:95], v[128:131], v[160:163], v[92:95]
	v_mfma_f32_16x16x32_bf16 v[84:87], v[136:139], v[160:163], v[84:87]
	s_waitcnt lgkmcnt(1)
	v_mfma_f32_16x16x32_bf16 v[76:79], v[128:131], v[168:171], v[76:79]
	v_mfma_f32_16x16x32_bf16 v[68:71], v[136:139], v[168:171], v[68:71]
	v_mfma_f32_16x16x32_bf16 v[124:127], v[132:135], v[148:151], v[124:127]
	v_mfma_f32_16x16x32_bf16 v[116:119], v[140:143], v[148:151], v[116:119]
	v_mfma_f32_16x16x32_bf16 v[108:111], v[132:135], v[156:159], v[108:111]
	v_mfma_f32_16x16x32_bf16 v[100:103], v[140:143], v[156:159], v[100:103]
	v_mfma_f32_16x16x32_bf16 v[92:95], v[132:135], v[164:167], v[92:95]
	v_mfma_f32_16x16x32_bf16 v[84:87], v[140:143], v[164:167], v[84:87]
	s_waitcnt lgkmcnt(0)
	v_mfma_f32_16x16x32_bf16 v[76:79], v[132:135], v[172:175], v[76:79]
	v_mfma_f32_16x16x32_bf16 v[68:71], v[140:143], v[172:175], v[68:71]
	s_barrier
	s_add_i32 s40, 0, 0x1c000
	s_add_i32 s41, s68, s33
	v_add_u32_e32 v204, s40, v183
	v_lshl_add_u64 v[208:209], v[208:209], 0, s[96:97]
	s_mov_b32 m0, s41
	ds_read_b128 v[176:179], v204
	ds_read_b128 v[196:199], v204 offset:1024
	ds_read_b128 v[200:203], v204 offset:2048
	ds_read_b128 v[204:207], v204 offset:3072
	global_load_lds_dwordx4 v[208:209], off
	v_lshl_add_u64 v[208:209], v[210:211], 0, s[96:97]
	s_add_i32 m0, s41, 0x2000
	s_nop 0
	global_load_lds_dwordx4 v[208:209], off
	s_barrier
	s_waitcnt lgkmcnt(3)
	v_mfma_f32_16x16x32_bf16 v[120:123], v[176:179], v[144:147], v[120:123]
	s_waitcnt lgkmcnt(1)
	v_mfma_f32_16x16x32_bf16 v[112:115], v[200:203], v[144:147], v[112:115]
	v_mfma_f32_16x16x32_bf16 v[104:107], v[176:179], v[152:155], v[104:107]
	v_mfma_f32_16x16x32_bf16 v[96:99], v[200:203], v[152:155], v[96:99]
	v_mfma_f32_16x16x32_bf16 v[88:91], v[176:179], v[160:163], v[88:91]
	v_mfma_f32_16x16x32_bf16 v[80:83], v[200:203], v[160:163], v[80:83]
	v_mfma_f32_16x16x32_bf16 v[72:75], v[176:179], v[168:171], v[72:75]
	v_mfma_f32_16x16x32_bf16 v[64:67], v[200:203], v[168:171], v[64:67]
	v_mfma_f32_16x16x32_bf16 v[120:123], v[196:199], v[148:151], v[120:123]
	s_waitcnt lgkmcnt(0)
	v_mfma_f32_16x16x32_bf16 v[112:115], v[204:207], v[148:151], v[112:115]
	v_mfma_f32_16x16x32_bf16 v[104:107], v[196:199], v[156:159], v[104:107]
	v_mfma_f32_16x16x32_bf16 v[96:99], v[204:207], v[156:159], v[96:99]
	v_mfma_f32_16x16x32_bf16 v[88:91], v[196:199], v[164:167], v[88:91]
	v_mfma_f32_16x16x32_bf16 v[80:83], v[204:207], v[164:167], v[80:83]
	v_mfma_f32_16x16x32_bf16 v[72:75], v[196:199], v[172:175], v[72:75]
	v_mfma_f32_16x16x32_bf16 v[64:67], v[204:207], v[172:175], v[64:67]
	s_mov_b32 m0, s8
	v_lshl_add_u64 v[208:209], v[212:213], 0, s[96:97]
	s_barrier
	ds_read_b128 v[144:147], v239 offset:49152
	ds_read_b128 v[148:151], v239 offset:50176
	ds_read_b128 v[152:155], v239 offset:51200
	ds_read_b128 v[156:159], v239 offset:52224
	ds_read_b128 v[160:163], v239 offset:53248
	ds_read_b128 v[164:167], v239 offset:54272
	ds_read_b128 v[168:171], v239 offset:55296
	ds_read_b128 v[172:175], v239 offset:56320
	global_load_lds_dwordx4 v[208:209], off
	v_lshl_add_u64 v[208:209], v[214:215], 0, s[96:97]
	s_mov_b32 m0, s9
	s_nop 0
	global_load_lds_dwordx4 v[208:209], off
	s_barrier
	s_waitcnt lgkmcnt(7)
	v_mfma_f32_16x16x32_bf16 v[60:63], v[128:131], v[144:147], v[60:63]
	v_mfma_f32_16x16x32_bf16 v[52:55], v[136:139], v[144:147], v[52:55]
	s_waitcnt lgkmcnt(5)
	v_mfma_f32_16x16x32_bf16 v[44:47], v[128:131], v[152:155], v[44:47]
	v_mfma_f32_16x16x32_bf16 v[36:39], v[136:139], v[152:155], v[36:39]
	s_waitcnt lgkmcnt(3)
	v_mfma_f32_16x16x32_bf16 v[28:31], v[128:131], v[160:163], v[28:31]
	v_mfma_f32_16x16x32_bf16 v[20:23], v[136:139], v[160:163], v[20:23]
	s_waitcnt lgkmcnt(1)
	v_mfma_f32_16x16x32_bf16 v[12:15], v[128:131], v[168:171], v[12:15]
	v_mfma_f32_16x16x32_bf16 v[4:7], v[136:139], v[168:171], v[4:7]
	v_mfma_f32_16x16x32_bf16 v[60:63], v[132:135], v[148:151], v[60:63]
	v_mfma_f32_16x16x32_bf16 v[52:55], v[140:143], v[148:151], v[52:55]
	v_mfma_f32_16x16x32_bf16 v[44:47], v[132:135], v[156:159], v[44:47]
	v_mfma_f32_16x16x32_bf16 v[36:39], v[140:143], v[156:159], v[36:39]
	v_mfma_f32_16x16x32_bf16 v[28:31], v[132:135], v[164:167], v[28:31]
	v_mfma_f32_16x16x32_bf16 v[20:23], v[140:143], v[164:167], v[20:23]
	s_waitcnt lgkmcnt(0)
	v_mfma_f32_16x16x32_bf16 v[12:15], v[132:135], v[172:175], v[12:15]
	v_mfma_f32_16x16x32_bf16 v[4:7], v[140:143], v[172:175], v[4:7]
	s_barrier
	s_add_i32 s40, s40, s33
	v_lshl_add_u64 v[128:129], v[216:217], 0, s[96:97]
	s_mov_b32 m0, s40
	s_nop 0
	global_load_lds_dwordx4 v[128:129], off
	v_lshl_add_u64 v[128:129], v[218:219], 0, s[96:97]
	s_add_i32 m0, s40, 0x2000
	s_nop 0
	global_load_lds_dwordx4 v[128:129], off
	s_waitcnt vmcnt(6)
	s_barrier
	v_mfma_f32_16x16x32_bf16 v[56:59], v[176:179], v[144:147], v[56:59]
	v_mfma_f32_16x16x32_bf16 v[48:51], v[200:203], v[144:147], v[48:51]
	v_mfma_f32_16x16x32_bf16 v[40:43], v[176:179], v[152:155], v[40:43]
	v_mfma_f32_16x16x32_bf16 v[32:35], v[200:203], v[152:155], v[32:35]
	v_mfma_f32_16x16x32_bf16 v[24:27], v[176:179], v[160:163], v[24:27]
	v_mfma_f32_16x16x32_bf16 v[16:19], v[200:203], v[160:163], v[16:19]
	v_mfma_f32_16x16x32_bf16 v[8:11], v[176:179], v[168:171], v[8:11]
	v_mfma_f32_16x16x32_bf16 v[0:3], v[200:203], v[168:171], v[0:3]
	v_mfma_f32_16x16x32_bf16 v[56:59], v[196:199], v[148:151], v[56:59]
	v_mfma_f32_16x16x32_bf16 v[48:51], v[204:207], v[148:151], v[48:51]
	v_mfma_f32_16x16x32_bf16 v[40:43], v[196:199], v[156:159], v[40:43]
	v_mfma_f32_16x16x32_bf16 v[32:35], v[204:207], v[156:159], v[32:35]
	v_mfma_f32_16x16x32_bf16 v[24:27], v[196:199], v[164:167], v[24:27]
	v_mfma_f32_16x16x32_bf16 v[16:19], v[204:207], v[164:167], v[16:19]
	v_mfma_f32_16x16x32_bf16 v[8:11], v[196:199], v[172:175], v[8:11]
	v_mfma_f32_16x16x32_bf16 v[0:3], v[204:207], v[172:175], v[0:3]
	s_add_u32 s0, s0, 0x100
	s_addc_u32 s1, s1, 0
	s_add_u32 s70, s70, 0x100
	s_addc_u32 s71, s71, 0
	s_cmp_ge_u32 s72, s7
	s_mov_b32 s40, s72
	s_barrier
	s_cbranch_scc0 .LBB0_141
	v_lshl_add_u32 v196, s19, 8, v181
	s_cmp_lt_i32 s78, 2
	s_mov_b64 s[0:1], -1
	s_cbranch_scc1 .LBB0_223
	s_cmp_gt_i32 s78, 2
	s_cbranch_scc0 .LBB0_220
	s_lshl_b32 s0, s18, 8
	s_ashr_i32 s68, s18, 1
	s_and_b32 s0, s0, 0x100
	s_cmp_lt_i32 s68, 2
	v_or_b32_e32 v148, s0, v238
	s_cselect_b64 s[0:1], -1, 0
	s_lshl_b32 s40, s68, 9
	s_add_i32 s80, s40, 0xfffffc00
	v_readlane_b32 s48, v241, 0
	s_lshl_b64 s[70:71], s[80:81], 2
	v_readlane_b32 s62, v241, 14
	v_readlane_b32 s63, v241, 15
	s_add_u32 s69, s62, s70
	s_addc_u32 s80, s63, s71
	s_ashr_i32 s41, s40, 31
	v_readlane_b32 s58, v241, 10
	s_lshl_b64 s[40:41], s[40:41], 2
	v_readlane_b32 s59, v241, 11
	s_add_u32 s99, s58, s40
	s_mov_b32 s83, s82
	s_addc_u32 s82, s59, s41
	s_cmp_lt_i32 s68, 4
	s_cselect_b64 s[72:73], -1, 0
	s_cmp_gt_i32 s68, 3
	s_cselect_b64 s[70:71], -1, 0
	v_mov_b32_e32 v132, 0
	s_and_b64 vcc, exec, s[70:71]
	v_lshlrev_b32_e32 v136, 2, v148
	v_mov_b32_e32 v140, 0
	v_mov_b32_e32 v141, v132
	v_mov_b32_e32 v142, 0
	v_mov_b32_e32 v143, 0
	v_readlane_b32 s49, v241, 1
	v_readlane_b32 s50, v241, 2
	v_readlane_b32 s51, v241, 3
	v_readlane_b32 s52, v241, 4
	v_readlane_b32 s53, v241, 5
	v_readlane_b32 s54, v241, 6
	v_readlane_b32 s55, v241, 7
	v_readlane_b32 s56, v241, 8
	v_readlane_b32 s57, v241, 9
	v_readlane_b32 s60, v241, 12
	v_readlane_b32 s61, v241, 13
	s_cbranch_vccnz .LBB0_146
	s_and_b64 s[40:41], s[0:1], exec
	s_cselect_b32 s41, s82, s80
	s_cselect_b32 s40, s99, s69
	global_load_dwordx4 v[140:143], v136, s[40:41]
